# acquire-side fence after the row-panel arrival spin no longer writes back L2 (invalidate only)
# speedup vs baseline: 1.0046x; 1.0031x over previous
; __device__ __forceinline__ int tidx() { int t = threadIdx.x; asm volatile("" : "+v"(t)); return t; }
; __global__ void __launch_bounds__(512, 2) mk_fwd(Params p) {
;     ...
;                     __syncthreads();
;                     if (tidx() == 0) { __threadfence(); __hip_atomic_fetch_add(cnt, 1u, __ATOMIC_RELAXED, __HIP_MEMORY_SCOPE_AGENT);
;                         while (__hip_atomic_load(cnt, __ATOMIC_RELAXED, __HIP_MEMORY_SCOPE_AGENT) < 8u) __builtin_amdgcn_s_sleep(2);
;                         __threadfence(); }
;                     __syncthreads();
;                     const int tid2 = tidx(), lane2 = tid2 & 63, wave2 = __builtin_amdgcn_readfirstlane(tid2 >> 6);
;                     const float* g = p.in[s == 1 ? 4 : (s == 11 ? 34 : 38)] + l * DM;
;                     row_phase(H, nullptr, (ph == NPH - 2) ? p.out : nullptr, XB, RS, g, s == 11 ? 1.0f : 0.5f, wave2, lane2, un.pm * 256 + un.pn * 32, 32);
.LBB0_668:
	s_sleep 2
	global_load_dword v0, v137, s[10:11] sc1
	s_waitcnt vmcnt(0)
	v_cmp_gt_u32_e32 vcc, 8, v0
	s_cbranch_vccnz .LBB0_668
.LBB0_669:
	buffer_inv sc1
.LBB0_670:
	s_or_b64 exec, exec, s[6:7]
	s_and_b64 s[6:7], s[8:9], exec
	s_cselect_b32 s5, 34, 38
	s_and_b64 s[0:1], s[0:1], exec
	s_cselect_b32 s0, 4, s5
	s_lshl_b32 s1, s0, 3
	v_mov_b32_e32 v0, v182
	s_barrier
	s_load_dwordx2 s[6:7], s[84:85], s1 offset:0x0
	s_lshl_b32 s1, s4, 8
	s_lshl_b32 s10, s22, 5
	s_add_i32 s1, s1, s10
	s_cmp_lt_i32 s1, 0
	v_readfirstlane_b32 s0, v0
	s_mov_b32 s5, 8
	s_cselect_b64 s[10:11], -1, 0
	s_cmp_gt_i32 s1, -1
	s_mov_b32 s12, s1
	s_cbranch_scc1 .LBB0_672
	s_mov_b32 s5, s2
	s_lshl_b32 s12, s5, 3
	s_movk_i32 s5, 0x800
